# phase-10 epilogue: same hoist + dwordx4 pairing as phase 14
# speedup vs baseline: 1.0195x; 1.0040x over previous
.LBB0_2297:
	s_lshl_b32 s28, s50, 8
	v_add_u32_e32 v140, s28, v1
	v_ashrrev_i32_e32 v141, 31, v140
	s_nop 15
	s_nop 15
	v_bfe_u32 v234, v206, 4, 1
	v_mul_u32_u24_e32 v234, 24, v234
	v_mov_b32_e32 v235, 0
	v_lshl_add_u64 v[150:151], v[140:141], 2, s[18:19]
	global_load_dword v149, v[150:151], off
	global_load_dword v236, v[150:151], off
	global_load_dword v237, v[150:151], off offset:64
	global_load_dword v238, v[150:151], off offset:128
	global_load_dword v239, v[150:151], off offset:192
	global_load_dword v240, v[150:151], off offset:512
	global_load_dword v241, v[150:151], off offset:576
	global_load_dword v242, v[150:151], off offset:640
	global_load_dword v243, v[150:151], off offset:704
	s_mulk_i32 s10, 0x2100
	v_lshl_add_u64 v[152:153], v[140:141], 0, s[10:11]
	v_lshlrev_b64 v[152:153], 10, v[152:153]
	s_lshl_b32 s26, s49, 9
	s_mov_b32 s27, s11
	v_lshl_add_u64 v[152:153], s[16:17], 0, v[152:153]
	v_lshl_add_u64 v[152:153], v[152:153], 0, s[26:27]
	v_lshl_add_u64 v[152:153], v[152:153], 0, v[134:135]
	s_andn2_b64 vcc, exec, s[24:25]
	s_mov_b64 s[24:25], -1
	s_waitcnt vmcnt(0)
	v_mul_f32_e32 v154, 0x3e0293ee, v149
	v_pk_mul_f32 v[126:127], v[126:127], v[154:155] op_sel_hi:[1,0]
	v_pk_mul_f32 v[128:129], v[128:129], v[154:155] op_sel_hi:[1,0]
	v_cvt_pk_bf16_f32 v224, v126, v127
	s_nop 0
	v_cvt_pk_bf16_f32 v225, v128, v129
	s_nop 0
	v_mov_b32_e32 v126, v236
	s_nop 0
	v_mul_f32_e32 v126, 0x3e0293ee, v126
	v_pk_mul_f32 v[122:123], v[122:123], v[126:127] op_sel_hi:[1,0]
	v_pk_mul_f32 v[124:125], v[124:125], v[126:127] op_sel_hi:[1,0]
	v_cvt_pk_bf16_f32 v226, v122, v123
	s_nop 0
	v_cvt_pk_bf16_f32 v227, v124, v125
	s_nop 1
	v_permlane16_swap_b32_e32 v224, v226
	v_permlane16_swap_b32_e32 v225, v227
	v_lshl_add_u64 v[232:233], v[152:153], 0, v[234:235]
	global_store_dwordx4 v[232:233], v[224:227], off
	v_mov_b32_e32 v122, v236
	s_nop 0
	v_mul_f32_e32 v122, 0x3e0293ee, v122
	v_pk_mul_f32 v[118:119], v[118:119], v[122:123] op_sel_hi:[1,0]
	v_pk_mul_f32 v[120:121], v[120:121], v[122:123] op_sel_hi:[1,0]
	v_cvt_pk_bf16_f32 v228, v118, v119
	s_nop 0
	v_cvt_pk_bf16_f32 v229, v120, v121
	s_nop 0
	v_mov_b32_e32 v122, v236
	v_add_u32_e32 v118, s28, v143
	v_ashrrev_i32_e32 v119, 31, v118
	v_lshl_add_u64 v[120:121], v[118:119], 2, s[18:19]
	s_nop 0
	v_mul_f32_e32 v122, 0x3e0293ee, v122
	v_pk_mul_f32 v[110:111], v[110:111], v[122:123] op_sel_hi:[1,0]
	v_pk_mul_f32 v[112:113], v[112:113], v[122:123] op_sel_hi:[1,0]
	v_cvt_pk_bf16_f32 v230, v110, v111
	s_nop 0
	v_cvt_pk_bf16_f32 v231, v112, v113
	s_nop 1
	v_permlane16_swap_b32_e32 v228, v230
	v_permlane16_swap_b32_e32 v229, v231
	v_lshl_add_u64 v[232:233], v[152:153], 0, v[234:235]
	global_store_dwordx4 v[232:233], v[228:231], off offset:256
	v_mov_b32_e32 v112, v237
	v_lshl_add_u64 v[110:111], v[118:119], 0, s[10:11]
	v_lshlrev_b64 v[110:111], 10, v[110:111]
	v_lshl_add_u64 v[110:111], s[16:17], 0, v[110:111]
	v_lshl_add_u64 v[110:111], v[110:111], 0, s[26:27]
	v_lshl_add_u64 v[110:111], v[110:111], 0, v[134:135]
	s_nop 0
	v_mul_f32_e32 v112, 0x3e0293ee, v112
	v_pk_mul_f32 v[116:117], v[116:117], v[112:113] op_sel_hi:[1,0]
	v_pk_mul_f32 v[112:113], v[114:115], v[112:113] op_sel_hi:[1,0]
	s_nop 0
	v_cvt_pk_bf16_f32 v224, v112, v113
	v_cvt_pk_bf16_f32 v225, v116, v117
	s_nop 0
	v_mov_b32_e32 v112, v237
	s_nop 0
	v_mul_f32_e32 v112, 0x3e0293ee, v112
	v_pk_mul_f32 v[106:107], v[106:107], v[112:113] op_sel_hi:[1,0]
	v_pk_mul_f32 v[108:109], v[108:109], v[112:113] op_sel_hi:[1,0]
	v_cvt_pk_bf16_f32 v226, v106, v107
	s_nop 0
	v_cvt_pk_bf16_f32 v227, v108, v109
	s_nop 1
	v_permlane16_swap_b32_e32 v224, v226
	v_permlane16_swap_b32_e32 v225, v227
	v_lshl_add_u64 v[232:233], v[110:111], 0, v[234:235]
	global_store_dwordx4 v[232:233], v[224:227], off
	v_mov_b32_e32 v106, v237
	s_nop 0
	v_mul_f32_e32 v106, 0x3e0293ee, v106
	v_pk_mul_f32 v[102:103], v[102:103], v[106:107] op_sel_hi:[1,0]
	v_pk_mul_f32 v[104:105], v[104:105], v[106:107] op_sel_hi:[1,0]
	v_cvt_pk_bf16_f32 v228, v102, v103
	s_nop 0
	v_cvt_pk_bf16_f32 v229, v104, v105
	s_nop 0
	v_mov_b32_e32 v106, v237
	v_add_u32_e32 v102, s28, v144
	v_ashrrev_i32_e32 v103, 31, v102
	v_lshl_add_u64 v[104:105], v[102:103], 2, s[18:19]
	s_nop 0
	v_mul_f32_e32 v106, 0x3e0293ee, v106
	v_pk_mul_f32 v[94:95], v[94:95], v[106:107] op_sel_hi:[1,0]
	v_pk_mul_f32 v[96:97], v[96:97], v[106:107] op_sel_hi:[1,0]
	v_cvt_pk_bf16_f32 v230, v94, v95
	s_nop 0
	v_cvt_pk_bf16_f32 v231, v96, v97
	s_nop 1
	v_permlane16_swap_b32_e32 v228, v230
	v_permlane16_swap_b32_e32 v229, v231
	v_lshl_add_u64 v[232:233], v[110:111], 0, v[234:235]
	global_store_dwordx4 v[232:233], v[228:231], off offset:256
	v_mov_b32_e32 v96, v238
	v_lshl_add_u64 v[94:95], v[102:103], 0, s[10:11]
	v_lshlrev_b64 v[94:95], 10, v[94:95]
	v_lshl_add_u64 v[94:95], s[16:17], 0, v[94:95]
	v_lshl_add_u64 v[94:95], v[94:95], 0, s[26:27]
	v_lshl_add_u64 v[94:95], v[94:95], 0, v[134:135]
	s_nop 0
	v_mul_f32_e32 v96, 0x3e0293ee, v96
	v_pk_mul_f32 v[100:101], v[100:101], v[96:97] op_sel_hi:[1,0]
	v_pk_mul_f32 v[96:97], v[98:99], v[96:97] op_sel_hi:[1,0]
	s_nop 0
	v_cvt_pk_bf16_f32 v224, v96, v97
	v_cvt_pk_bf16_f32 v225, v100, v101
	s_nop 0
	v_mov_b32_e32 v96, v238
	s_nop 0
	v_mul_f32_e32 v96, 0x3e0293ee, v96
	v_pk_mul_f32 v[90:91], v[90:91], v[96:97] op_sel_hi:[1,0]
	v_pk_mul_f32 v[92:93], v[92:93], v[96:97] op_sel_hi:[1,0]
	v_cvt_pk_bf16_f32 v226, v90, v91
	s_nop 0
	v_cvt_pk_bf16_f32 v227, v92, v93
	s_nop 1
	v_permlane16_swap_b32_e32 v224, v226
	v_permlane16_swap_b32_e32 v225, v227
	v_lshl_add_u64 v[232:233], v[94:95], 0, v[234:235]
	global_store_dwordx4 v[232:233], v[224:227], off
	v_mov_b32_e32 v90, v238
	s_nop 0
	v_mul_f32_e32 v90, 0x3e0293ee, v90
	v_pk_mul_f32 v[86:87], v[86:87], v[90:91] op_sel_hi:[1,0]
	v_pk_mul_f32 v[88:89], v[88:89], v[90:91] op_sel_hi:[1,0]
	v_cvt_pk_bf16_f32 v228, v86, v87
	s_nop 0
	v_cvt_pk_bf16_f32 v229, v88, v89
	s_nop 0
	v_mov_b32_e32 v90, v238
	v_add_u32_e32 v86, s28, v145
	v_ashrrev_i32_e32 v87, 31, v86
	v_lshl_add_u64 v[88:89], v[86:87], 2, s[18:19]
	s_nop 0
	v_mul_f32_e32 v90, 0x3e0293ee, v90
	v_pk_mul_f32 v[78:79], v[78:79], v[90:91] op_sel_hi:[1,0]
	v_pk_mul_f32 v[80:81], v[80:81], v[90:91] op_sel_hi:[1,0]
	v_cvt_pk_bf16_f32 v230, v78, v79
	s_nop 0
	v_cvt_pk_bf16_f32 v231, v80, v81
	s_nop 1
	v_permlane16_swap_b32_e32 v228, v230
	v_permlane16_swap_b32_e32 v229, v231
	v_lshl_add_u64 v[232:233], v[94:95], 0, v[234:235]
	global_store_dwordx4 v[232:233], v[228:231], off offset:256
	v_mov_b32_e32 v80, v239
	v_lshl_add_u64 v[78:79], v[86:87], 0, s[10:11]
	v_lshlrev_b64 v[78:79], 10, v[78:79]
	v_lshl_add_u64 v[78:79], s[16:17], 0, v[78:79]
	v_lshl_add_u64 v[78:79], v[78:79], 0, s[26:27]
	v_lshl_add_u64 v[78:79], v[78:79], 0, v[134:135]
	s_nop 0
	v_mul_f32_e32 v80, 0x3e0293ee, v80
	v_pk_mul_f32 v[84:85], v[84:85], v[80:81] op_sel_hi:[1,0]
	v_pk_mul_f32 v[80:81], v[82:83], v[80:81] op_sel_hi:[1,0]
	s_nop 0
	v_cvt_pk_bf16_f32 v224, v80, v81
	v_cvt_pk_bf16_f32 v225, v84, v85
	s_nop 0
	v_mov_b32_e32 v80, v239
	s_nop 0
	v_mul_f32_e32 v80, 0x3e0293ee, v80
	v_pk_mul_f32 v[74:75], v[74:75], v[80:81] op_sel_hi:[1,0]
	v_pk_mul_f32 v[76:77], v[76:77], v[80:81] op_sel_hi:[1,0]
	v_cvt_pk_bf16_f32 v226, v74, v75
	s_nop 0
	v_cvt_pk_bf16_f32 v227, v76, v77
	s_nop 1
	v_permlane16_swap_b32_e32 v224, v226
	v_permlane16_swap_b32_e32 v225, v227
	v_lshl_add_u64 v[232:233], v[78:79], 0, v[234:235]
	global_store_dwordx4 v[232:233], v[224:227], off
	v_mov_b32_e32 v74, v239
	s_nop 0
	v_mul_f32_e32 v74, 0x3e0293ee, v74
	v_pk_mul_f32 v[70:71], v[70:71], v[74:75] op_sel_hi:[1,0]
	v_pk_mul_f32 v[72:73], v[72:73], v[74:75] op_sel_hi:[1,0]
	v_cvt_pk_bf16_f32 v228, v70, v71
	s_nop 0
	v_cvt_pk_bf16_f32 v229, v72, v73
	s_nop 0
	v_mov_b32_e32 v74, v239
	v_add_u32_e32 v70, 0x80, v140
	v_ashrrev_i32_e32 v71, 31, v70
	v_lshl_add_u64 v[72:73], v[70:71], 2, s[18:19]
	s_nop 0
	v_mul_f32_e32 v74, 0x3e0293ee, v74
	v_pk_mul_f32 v[66:67], v[66:67], v[74:75] op_sel_hi:[1,0]
	v_pk_mul_f32 v[68:69], v[68:69], v[74:75] op_sel_hi:[1,0]
	v_cvt_pk_bf16_f32 v230, v66, v67
	s_nop 0
	v_cvt_pk_bf16_f32 v231, v68, v69
	s_nop 1
	v_permlane16_swap_b32_e32 v228, v230
	v_permlane16_swap_b32_e32 v229, v231
	v_lshl_add_u64 v[232:233], v[78:79], 0, v[234:235]
	global_store_dwordx4 v[232:233], v[228:231], off offset:256
	v_mov_b32_e32 v68, v240
	v_lshl_add_u64 v[66:67], v[70:71], 0, s[10:11]
	v_lshlrev_b64 v[66:67], 10, v[66:67]
	v_lshl_add_u64 v[66:67], s[16:17], 0, v[66:67]
	v_lshl_add_u64 v[66:67], v[66:67], 0, s[26:27]
	v_lshl_add_u64 v[66:67], v[66:67], 0, v[134:135]
	s_nop 0
	v_mul_f32_e32 v68, 0x3e0293ee, v68
	v_pk_mul_f32 v[62:63], v[62:63], v[68:69] op_sel_hi:[1,0]
	v_pk_mul_f32 v[64:65], v[64:65], v[68:69] op_sel_hi:[1,0]
	v_cvt_pk_bf16_f32 v224, v62, v63
	s_nop 0
	v_cvt_pk_bf16_f32 v225, v64, v65
	s_nop 0
	v_mov_b32_e32 v62, v240
	s_nop 0
	v_mul_f32_e32 v62, 0x3e0293ee, v62
	v_pk_mul_f32 v[58:59], v[58:59], v[62:63] op_sel_hi:[1,0]
	v_pk_mul_f32 v[60:61], v[60:61], v[62:63] op_sel_hi:[1,0]
	v_cvt_pk_bf16_f32 v226, v58, v59
	s_nop 0
	v_cvt_pk_bf16_f32 v227, v60, v61
	s_nop 1
	v_permlane16_swap_b32_e32 v224, v226
	v_permlane16_swap_b32_e32 v225, v227
	v_lshl_add_u64 v[232:233], v[66:67], 0, v[234:235]
	global_store_dwordx4 v[232:233], v[224:227], off
	v_mov_b32_e32 v58, v240
	s_nop 0
	v_mul_f32_e32 v58, 0x3e0293ee, v58
	v_pk_mul_f32 v[54:55], v[54:55], v[58:59] op_sel_hi:[1,0]
	v_pk_mul_f32 v[56:57], v[56:57], v[58:59] op_sel_hi:[1,0]
	v_cvt_pk_bf16_f32 v228, v54, v55
	s_nop 0
	v_cvt_pk_bf16_f32 v229, v56, v57
	s_nop 0
	v_mov_b32_e32 v58, v240
	v_add_u32_e32 v54, 0x90, v140
	v_ashrrev_i32_e32 v55, 31, v54
	v_lshl_add_u64 v[56:57], v[54:55], 2, s[18:19]
	s_nop 0
	v_mul_f32_e32 v58, 0x3e0293ee, v58
	v_pk_mul_f32 v[46:47], v[46:47], v[58:59] op_sel_hi:[1,0]
	v_pk_mul_f32 v[48:49], v[48:49], v[58:59] op_sel_hi:[1,0]
	v_cvt_pk_bf16_f32 v230, v46, v47
	s_nop 0
	v_cvt_pk_bf16_f32 v231, v48, v49
	s_nop 1
	v_permlane16_swap_b32_e32 v228, v230
	v_permlane16_swap_b32_e32 v229, v231
	v_lshl_add_u64 v[232:233], v[66:67], 0, v[234:235]
	global_store_dwordx4 v[232:233], v[228:231], off offset:256
	v_mov_b32_e32 v48, v241
	v_lshl_add_u64 v[46:47], v[54:55], 0, s[10:11]
	v_lshlrev_b64 v[46:47], 10, v[46:47]
	v_lshl_add_u64 v[46:47], s[16:17], 0, v[46:47]
	v_lshl_add_u64 v[46:47], v[46:47], 0, s[26:27]
	v_lshl_add_u64 v[46:47], v[46:47], 0, v[134:135]
	s_nop 0
	v_mul_f32_e32 v48, 0x3e0293ee, v48
	v_pk_mul_f32 v[52:53], v[52:53], v[48:49] op_sel_hi:[1,0]
	v_pk_mul_f32 v[48:49], v[50:51], v[48:49] op_sel_hi:[1,0]
	s_nop 0
	v_cvt_pk_bf16_f32 v224, v48, v49
	v_cvt_pk_bf16_f32 v225, v52, v53
	s_nop 0
	v_mov_b32_e32 v48, v241
	s_nop 0
	v_mul_f32_e32 v48, 0x3e0293ee, v48
	v_pk_mul_f32 v[42:43], v[42:43], v[48:49] op_sel_hi:[1,0]
	v_pk_mul_f32 v[44:45], v[44:45], v[48:49] op_sel_hi:[1,0]
	v_cvt_pk_bf16_f32 v226, v42, v43
	s_nop 0
	v_cvt_pk_bf16_f32 v227, v44, v45
	s_nop 1
	v_permlane16_swap_b32_e32 v224, v226
	v_permlane16_swap_b32_e32 v225, v227
	v_lshl_add_u64 v[232:233], v[46:47], 0, v[234:235]
	global_store_dwordx4 v[232:233], v[224:227], off
	v_mov_b32_e32 v42, v241
	s_nop 0
	v_mul_f32_e32 v42, 0x3e0293ee, v42
	v_pk_mul_f32 v[38:39], v[38:39], v[42:43] op_sel_hi:[1,0]
	v_pk_mul_f32 v[40:41], v[40:41], v[42:43] op_sel_hi:[1,0]
	v_cvt_pk_bf16_f32 v228, v38, v39
	s_nop 0
	v_cvt_pk_bf16_f32 v229, v40, v41
	s_nop 0
	v_mov_b32_e32 v42, v241
	v_add_u32_e32 v38, 0xa0, v140
	v_ashrrev_i32_e32 v39, 31, v38
	v_lshl_add_u64 v[40:41], v[38:39], 2, s[18:19]
	s_nop 0
	v_mul_f32_e32 v42, 0x3e0293ee, v42
	v_pk_mul_f32 v[30:31], v[30:31], v[42:43] op_sel_hi:[1,0]
	v_pk_mul_f32 v[32:33], v[32:33], v[42:43] op_sel_hi:[1,0]
	v_cvt_pk_bf16_f32 v230, v30, v31
	s_nop 0
	v_cvt_pk_bf16_f32 v231, v32, v33
	s_nop 1
	v_permlane16_swap_b32_e32 v228, v230
	v_permlane16_swap_b32_e32 v229, v231
	v_lshl_add_u64 v[232:233], v[46:47], 0, v[234:235]
	global_store_dwordx4 v[232:233], v[228:231], off offset:256
	v_mov_b32_e32 v32, v242
	v_lshl_add_u64 v[30:31], v[38:39], 0, s[10:11]
	v_lshlrev_b64 v[30:31], 10, v[30:31]
	v_lshl_add_u64 v[30:31], s[16:17], 0, v[30:31]
	v_lshl_add_u64 v[30:31], v[30:31], 0, s[26:27]
	v_lshl_add_u64 v[30:31], v[30:31], 0, v[134:135]
	s_nop 0
	v_mul_f32_e32 v32, 0x3e0293ee, v32
	v_pk_mul_f32 v[36:37], v[36:37], v[32:33] op_sel_hi:[1,0]
	v_pk_mul_f32 v[32:33], v[34:35], v[32:33] op_sel_hi:[1,0]
	s_nop 0
	v_cvt_pk_bf16_f32 v224, v32, v33
	v_cvt_pk_bf16_f32 v225, v36, v37
	s_nop 0
	v_mov_b32_e32 v32, v242
	s_nop 0
	v_mul_f32_e32 v32, 0x3e0293ee, v32
	v_pk_mul_f32 v[26:27], v[26:27], v[32:33] op_sel_hi:[1,0]
	v_pk_mul_f32 v[28:29], v[28:29], v[32:33] op_sel_hi:[1,0]
	v_cvt_pk_bf16_f32 v226, v26, v27
	s_nop 0
	v_cvt_pk_bf16_f32 v227, v28, v29
	s_nop 1
	v_permlane16_swap_b32_e32 v224, v226
	v_permlane16_swap_b32_e32 v225, v227
	v_lshl_add_u64 v[232:233], v[30:31], 0, v[234:235]
	global_store_dwordx4 v[232:233], v[224:227], off
	v_mov_b32_e32 v26, v242
	s_nop 0
	v_mul_f32_e32 v26, 0x3e0293ee, v26
	v_pk_mul_f32 v[22:23], v[22:23], v[26:27] op_sel_hi:[1,0]
	v_pk_mul_f32 v[24:25], v[24:25], v[26:27] op_sel_hi:[1,0]
	v_cvt_pk_bf16_f32 v228, v22, v23
	s_nop 0
	v_cvt_pk_bf16_f32 v229, v24, v25
	s_nop 0
	v_mov_b32_e32 v26, v242
	v_add_u32_e32 v22, 0xb0, v140
	v_ashrrev_i32_e32 v23, 31, v22
	v_lshl_add_u64 v[24:25], v[22:23], 2, s[18:19]
	s_nop 0
	v_mul_f32_e32 v26, 0x3e0293ee, v26
	v_pk_mul_f32 v[14:15], v[14:15], v[26:27] op_sel_hi:[1,0]
	v_pk_mul_f32 v[16:17], v[16:17], v[26:27] op_sel_hi:[1,0]
	v_cvt_pk_bf16_f32 v230, v14, v15
	s_nop 0
	v_cvt_pk_bf16_f32 v231, v16, v17
	s_nop 1
	v_permlane16_swap_b32_e32 v228, v230
	v_permlane16_swap_b32_e32 v229, v231
	v_lshl_add_u64 v[232:233], v[30:31], 0, v[234:235]
	global_store_dwordx4 v[232:233], v[228:231], off offset:256
	v_mov_b32_e32 v16, v243
	v_lshl_add_u64 v[14:15], v[22:23], 0, s[10:11]
	v_lshlrev_b64 v[14:15], 10, v[14:15]
	v_lshl_add_u64 v[14:15], s[16:17], 0, v[14:15]
	v_lshl_add_u64 v[14:15], v[14:15], 0, s[26:27]
	v_lshl_add_u64 v[14:15], v[14:15], 0, v[134:135]
	s_nop 0
	v_mul_f32_e32 v16, 0x3e0293ee, v16
	v_pk_mul_f32 v[20:21], v[20:21], v[16:17] op_sel_hi:[1,0]
	v_pk_mul_f32 v[16:17], v[18:19], v[16:17] op_sel_hi:[1,0]
	s_nop 0
	v_cvt_pk_bf16_f32 v224, v16, v17
	v_cvt_pk_bf16_f32 v225, v20, v21
	s_nop 0
	v_mov_b32_e32 v16, v243
	s_nop 0
	v_mul_f32_e32 v16, 0x3e0293ee, v16
	v_pk_mul_f32 v[10:11], v[10:11], v[16:17] op_sel_hi:[1,0]
	v_pk_mul_f32 v[12:13], v[12:13], v[16:17] op_sel_hi:[1,0]
	v_cvt_pk_bf16_f32 v226, v10, v11
	s_nop 0
	v_cvt_pk_bf16_f32 v227, v12, v13
	s_nop 1
	v_permlane16_swap_b32_e32 v224, v226
	v_permlane16_swap_b32_e32 v225, v227
	v_lshl_add_u64 v[232:233], v[14:15], 0, v[234:235]
	global_store_dwordx4 v[232:233], v[224:227], off
	v_mov_b32_e32 v10, v243
	s_nop 0
	v_mul_f32_e32 v10, 0x3e0293ee, v10
	v_pk_mul_f32 v[6:7], v[6:7], v[10:11] op_sel_hi:[1,0]
	v_pk_mul_f32 v[8:9], v[8:9], v[10:11] op_sel_hi:[1,0]
	v_cvt_pk_bf16_f32 v228, v6, v7
	s_nop 0
	v_cvt_pk_bf16_f32 v229, v8, v9
	s_nop 0
	v_mov_b32_e32 v6, v243
	s_nop 0
	v_mul_f32_e32 v6, 0x3e0293ee, v6
	v_pk_mul_f32 v[2:3], v[2:3], v[6:7] op_sel_hi:[1,0]
	v_pk_mul_f32 v[4:5], v[4:5], v[6:7] op_sel_hi:[1,0]
	v_cvt_pk_bf16_f32 v230, v2, v3
	s_nop 0
	v_cvt_pk_bf16_f32 v231, v4, v5
	s_nop 1
	v_permlane16_swap_b32_e32 v228, v230
	v_permlane16_swap_b32_e32 v229, v231
	v_lshl_add_u64 v[232:233], v[14:15], 0, v[234:235]
	global_store_dwordx4 v[232:233], v[228:231], off offset:256
	s_cbranch_vccnz .LBB0_2292
	s_andn2_b64 vcc, exec, s[12:13]
	s_cbranch_vccnz .LBB0_2291
	s_barrier
	s_branch .LBB0_2291
